# v13 plus up GEMM relu-squared epilogue: redundant canonicalizing v_max x,x,x removed (106 instructions)
# speedup vs baseline: 1.0004x; 1.0004x over previous
; #define G8_STAGE(bufoff, gbase, voff) do { _Pragma("unroll") for (int _i = 0; _i < 2; ++_i) \
;     __builtin_amdgcn_global_load_lds((const unsigned*)((const char*)(gbase) + (voff)[_i]), (LAS unsigned*)(lds + (bufoff) + ldsw + _i * 8192), 16, 0, 0); } while (0)
; #define G8_LDA(dst, b, h) do { _Pragma("unroll") for (int m = 0; m < 4; ++m) _Pragma("unroll") for (int k = 0; k < 2; ++k) dst[m][k] = *(const LAS bf16x8*)(lds + G8_SA(b, h) + aoff + m * 2048 + k * 1024); } while (0)
; #define G8_LDB(dst, b, h) do { _Pragma("unroll") for (int n = 0; n < 2; ++n) _Pragma("unroll") for (int k = 0; k < 2; ++k) dst[n][k] = *(const LAS bf16x8*)(lds + G8_SB(b, h) + boff + n * 2048 + k * 1024); } while (0)
; #define G8_MMA(ai, bj, At, Bt) do { __builtin_amdgcn_s_setprio(1); _Pragma("unroll") for (int m = 0; m < 4; ++m) _Pragma("unroll") for (int n = 0; n < 2; ++n) _Pragma("unroll") for (int k = 0; k < 2; ++k) \
;     acc[ai][bj][m][n] = __builtin_amdgcn_mfma_f32_16x16x32_bf16(Bt[n][k], At[m][k], acc[ai][bj][m][n], 0, 0, 0); __builtin_amdgcn_s_setprio(0); } while (0)
; #define G8_WAIT_L(n) asm volatile("s_waitcnt lgkmcnt(" #n ")" ::: "memory")
; #define G8_BAR __builtin_amdgcn_s_barrier()
; #define G8_SCHED __builtin_amdgcn_sched_barrier(0)
; template <class Epi, class Sched>
; __device__ __forceinline__ void gemm_phase(LAS unsigned char* lds, const Gemm g, const Sched& S, const Epi& E) {
;     ...
;       G8_LDB(B0, 0, 0); G8_SCHED; G8_LDA(At, 0, 0); G8_STAGE(G8_SA(1, 1), a1 + hstepA, voffA);
;       G8_WAIT_L(8); G8_BAR; G8_WAIT_L(0); G8_MMA(0, 0, At, B0); G8_BAR; G8_SCHED;
;       G8_LDB(B1, 0, 1); G8_STAGE(G8_SB(0, 0), b2, voffB);
;       G8_BAR; G8_WAIT_L(0); G8_MMA(0, 1, At, B1); G8_BAR;
;       G8_LDA(At, 0, 1); G8_STAGE(G8_SA(0, 0), a2, voffA);
;       G8_BAR; G8_WAIT_L(0); G8_MMA(1, 0, At, B0); G8_BAR; G8_SCHED;
.LBB0_2356:
	ds_read_b128 v[148:151], v145
	ds_read_b128 v[152:155], v145 offset:1024
	ds_read_b128 v[156:159], v145 offset:2048
	ds_read_b128 v[160:163], v145 offset:3072
	s_add_u32 s34, s30, 0xfffc0080
	s_addc_u32 s35, s31, -1
	s_cmp_eq_u32 s59, 12
	s_cselect_b32 s37, s17, s35
	s_cselect_b32 s36, s55, s34
	s_cselect_b32 s35, s15, s58
	s_cselect_b32 s34, s56, s57
	v_lshl_add_u64 v[140:141], s[30:31], 0, v[132:133]
	s_add_i32 m0, s43, 0xc000
	ds_read_b128 v[164:167], v146
	ds_read_b128 v[168:171], v146 offset:1024
	ds_read_b128 v[172:175], v146 offset:2048
	ds_read_b128 v[176:179], v146 offset:3072
	ds_read_b128 v[180:183], v146 offset:4096
	ds_read_b128 v[184:187], v146 offset:5120
	ds_read_b128 v[188:191], v146 offset:6144
	ds_read_b128 v[192:195], v146 offset:7168
	global_load_lds_dwordx4 v[140:141], off
	v_lshl_add_u64 v[140:141], s[30:31], 0, v[134:135]
	s_add_i32 m0, s43, 0xe000
	s_nop 0
	global_load_lds_dwordx4 v[140:141], off
	s_waitcnt lgkmcnt(8)
	s_barrier
	s_waitcnt lgkmcnt(0)
	s_setprio 1
	s_waitcnt lgkmcnt(0)
	v_mfma_f32_16x16x32_bf16 v[124:127], v[148:151], v[164:167], v[124:127]
	v_mfma_f32_16x16x32_bf16 v[120:123], v[156:159], v[164:167], v[120:123]
	v_mfma_f32_16x16x32_bf16 v[108:111], v[148:151], v[172:175], v[108:111]
	v_mfma_f32_16x16x32_bf16 v[104:107], v[156:159], v[172:175], v[104:107]
	v_mfma_f32_16x16x32_bf16 v[92:95], v[148:151], v[180:183], v[92:95]
	v_mfma_f32_16x16x32_bf16 v[88:91], v[156:159], v[180:183], v[88:91]
	v_mfma_f32_16x16x32_bf16 v[76:79], v[148:151], v[188:191], v[76:79]
	v_mfma_f32_16x16x32_bf16 v[72:75], v[156:159], v[188:191], v[72:75]
	v_mfma_f32_16x16x32_bf16 v[124:127], v[152:155], v[168:171], v[124:127]
	v_mfma_f32_16x16x32_bf16 v[120:123], v[160:163], v[168:171], v[120:123]
	v_mfma_f32_16x16x32_bf16 v[108:111], v[152:155], v[176:179], v[108:111]
	v_mfma_f32_16x16x32_bf16 v[104:107], v[160:163], v[176:179], v[104:107]
	v_mfma_f32_16x16x32_bf16 v[92:95], v[152:155], v[184:187], v[92:95]
	v_mfma_f32_16x16x32_bf16 v[88:91], v[160:163], v[184:187], v[88:91]
	v_mfma_f32_16x16x32_bf16 v[76:79], v[152:155], v[192:195], v[76:79]
	v_mfma_f32_16x16x32_bf16 v[72:75], v[160:163], v[192:195], v[72:75]
	s_setprio 0
	s_barrier
	s_add_i32 s60, s52, s40
	v_lshl_add_u64 v[140:141], s[34:35], 0, v[130:131]
	s_mov_b32 m0, s60
	ds_read_b128 v[196:199], v147
	ds_read_b128 v[200:203], v147 offset:1024
	ds_read_b128 v[204:207], v147 offset:2048
	ds_read_b128 v[208:211], v147 offset:3072
	global_load_lds_dwordx4 v[140:141], off
	v_lshl_add_u64 v[212:213], s[34:35], 0, v[128:129]
	s_add_i32 m0, s60, 0x2000
	s_nop 0
	global_load_lds_dwordx4 v[212:213], off
	s_barrier
	s_waitcnt lgkmcnt(0)
	s_setprio 1
	s_waitcnt lgkmcnt(0)
	v_mfma_f32_16x16x32_bf16 v[116:119], v[196:199], v[164:167], v[116:119]
	v_mfma_f32_16x16x32_bf16 v[112:115], v[204:207], v[164:167], v[112:115]
	v_mfma_f32_16x16x32_bf16 v[100:103], v[196:199], v[172:175], v[100:103]
	v_mfma_f32_16x16x32_bf16 v[96:99], v[204:207], v[172:175], v[96:99]
	v_mfma_f32_16x16x32_bf16 v[84:87], v[196:199], v[180:183], v[84:87]
	v_mfma_f32_16x16x32_bf16 v[80:83], v[204:207], v[180:183], v[80:83]
	v_mfma_f32_16x16x32_bf16 v[68:71], v[196:199], v[188:191], v[68:71]
	v_mfma_f32_16x16x32_bf16 v[64:67], v[204:207], v[188:191], v[64:67]
	v_mfma_f32_16x16x32_bf16 v[116:119], v[200:203], v[168:171], v[116:119]
	v_mfma_f32_16x16x32_bf16 v[112:115], v[208:211], v[168:171], v[112:115]
	v_mfma_f32_16x16x32_bf16 v[100:103], v[200:203], v[176:179], v[100:103]
	v_mfma_f32_16x16x32_bf16 v[96:99], v[208:211], v[176:179], v[96:99]
	v_mfma_f32_16x16x32_bf16 v[84:87], v[200:203], v[184:187], v[84:87]
	v_mfma_f32_16x16x32_bf16 v[80:83], v[208:211], v[184:187], v[80:83]
	v_mfma_f32_16x16x32_bf16 v[68:71], v[200:203], v[192:195], v[68:71]
	v_mfma_f32_16x16x32_bf16 v[64:67], v[208:211], v[192:195], v[64:67]
	s_setprio 0
	s_mov_b32 m0, s43
	v_lshl_add_u64 v[214:215], s[36:37], 0, v[130:131]
	s_barrier
	ds_read_b128 v[164:167], v146 offset:16384
	ds_read_b128 v[168:171], v146 offset:17408
	ds_read_b128 v[172:175], v146 offset:18432
	ds_read_b128 v[176:179], v146 offset:19456
	ds_read_b128 v[180:183], v146 offset:20480
	ds_read_b128 v[184:187], v146 offset:21504
	ds_read_b128 v[188:191], v146 offset:22528
	ds_read_b128 v[192:195], v146 offset:23552
	global_load_lds_dwordx4 v[214:215], off
	v_lshl_add_u64 v[216:217], s[36:37], 0, v[128:129]
	s_mov_b32 m0, s44
	s_nop 0
	global_load_lds_dwordx4 v[216:217], off
	s_barrier
	s_waitcnt lgkmcnt(0)
	s_setprio 1
	s_waitcnt lgkmcnt(0)
	v_mfma_f32_16x16x32_bf16 v[60:63], v[148:151], v[164:167], v[60:63]
	v_mfma_f32_16x16x32_bf16 v[56:59], v[156:159], v[164:167], v[56:59]
	v_mfma_f32_16x16x32_bf16 v[44:47], v[148:151], v[172:175], v[44:47]
	v_mfma_f32_16x16x32_bf16 v[40:43], v[156:159], v[172:175], v[40:43]
	v_mfma_f32_16x16x32_bf16 v[28:31], v[148:151], v[180:183], v[28:31]
	v_mfma_f32_16x16x32_bf16 v[24:27], v[156:159], v[180:183], v[24:27]
	v_mfma_f32_16x16x32_bf16 v[12:15], v[148:151], v[188:191], v[12:15]
	v_mfma_f32_16x16x32_bf16 v[8:11], v[156:159], v[188:191], v[8:11]
	v_mfma_f32_16x16x32_bf16 v[60:63], v[152:155], v[168:171], v[60:63]
	v_mfma_f32_16x16x32_bf16 v[56:59], v[160:163], v[168:171], v[56:59]
	v_mfma_f32_16x16x32_bf16 v[44:47], v[152:155], v[176:179], v[44:47]
	v_mfma_f32_16x16x32_bf16 v[40:43], v[160:163], v[176:179], v[40:43]
	v_mfma_f32_16x16x32_bf16 v[28:31], v[152:155], v[184:187], v[28:31]
	v_mfma_f32_16x16x32_bf16 v[24:27], v[160:163], v[184:187], v[24:27]
	v_mfma_f32_16x16x32_bf16 v[12:15], v[152:155], v[192:195], v[12:15]
	v_mfma_f32_16x16x32_bf16 v[8:11], v[160:163], v[192:195], v[8:11]
	s_setprio 0
	s_barrier
; #define G8_STAGE(bufoff, gbase, voff) do { _Pragma("unroll") for (int _i = 0; _i < 2; ++_i) \
;     __builtin_amdgcn_global_load_lds((const unsigned*)((const char*)(gbase) + (voff)[_i]), (LAS unsigned*)(lds + (bufoff) + ldsw + _i * 8192), 16, 0, 0); } while (0)
; #define G8_LDA(dst, b, h) do { _Pragma("unroll") for (int m = 0; m < 4; ++m) _Pragma("unroll") for (int k = 0; k < 2; ++k) dst[m][k] = *(const LAS bf16x8*)(lds + G8_SA(b, h) + aoff + m * 2048 + k * 1024); } while (0)
; #define G8_LDB(dst, b, h) do { _Pragma("unroll") for (int n = 0; n < 2; ++n) _Pragma("unroll") for (int k = 0; k < 2; ++k) dst[n][k] = *(const LAS bf16x8*)(lds + G8_SB(b, h) + boff + n * 2048 + k * 1024); } while (0)
; #define G8_MMA(ai, bj, At, Bt) do { __builtin_amdgcn_s_setprio(1); _Pragma("unroll") for (int m = 0; m < 4; ++m) _Pragma("unroll") for (int n = 0; n < 2; ++n) _Pragma("unroll") for (int k = 0; k < 2; ++k) \
;     acc[ai][bj][m][n] = __builtin_amdgcn_mfma_f32_16x16x32_bf16(Bt[n][k], At[m][k], acc[ai][bj][m][n], 0, 0, 0); __builtin_amdgcn_s_setprio(0); } while (0)
; #define G8_WAIT_V(n) asm volatile("s_waitcnt vmcnt(" #n ")" ::: "memory")
; #define G8_WAIT_L(n) asm volatile("s_waitcnt lgkmcnt(" #n ")" ::: "memory")
; #define G8_BAR __builtin_amdgcn_s_barrier()
; #define G8_SCHED __builtin_amdgcn_sched_barrier(0)
; template <class Epi, class Sched>
; __device__ __forceinline__ void gemm_phase(LAS unsigned char* lds, const Gemm g, const Sched& S, const Epi& E) {
;     ...
;       G8_STAGE(G8_SB(0, 1), b2 + hstepB, voffB);
;       G8_WAIT_V(6); G8_BAR; G8_MMA(1, 1, At, B1); G8_BAR;
;       G8_LDB(B0, 1, 0); G8_SCHED; G8_LDA(At, 1, 0); G8_STAGE(G8_SA(0, 1), a2 + hstepA, voffA);
;       G8_WAIT_L(8); G8_BAR; G8_WAIT_L(0); G8_MMA(0, 0, At, B0); G8_BAR; G8_SCHED;
;       G8_LDB(B1, 1, 1); G8_STAGE(G8_SB(1, 0), b3, voffB);
;       G8_BAR; G8_WAIT_L(0); G8_MMA(0, 1, At, B1); G8_BAR;
	s_add_u32 s60, s34, 0x40000
	s_addc_u32 s61, s35, 0
	s_add_i32 s62, s53, s40
	v_lshl_add_u64 v[148:149], s[60:61], 0, v[130:131]
	s_mov_b32 m0, s62
	s_nop 0
	global_load_lds_dwordx4 v[148:149], off
	v_lshl_add_u64 v[148:149], s[60:61], 0, v[128:129]
	s_add_i32 m0, s62, 0x2000
	s_nop 0
	global_load_lds_dwordx4 v[148:149], off
	s_waitcnt vmcnt(6)
	s_barrier
	s_setprio 1
	v_mfma_f32_16x16x32_bf16 v[52:55], v[196:199], v[164:167], v[52:55]
	v_mfma_f32_16x16x32_bf16 v[48:51], v[204:207], v[164:167], v[48:51]
	v_mfma_f32_16x16x32_bf16 v[36:39], v[196:199], v[172:175], v[36:39]
	v_mfma_f32_16x16x32_bf16 v[32:35], v[204:207], v[172:175], v[32:35]
	v_mfma_f32_16x16x32_bf16 v[20:23], v[196:199], v[180:183], v[20:23]
	v_mfma_f32_16x16x32_bf16 v[16:19], v[204:207], v[180:183], v[16:19]
	v_mfma_f32_16x16x32_bf16 v[4:7], v[196:199], v[188:191], v[4:7]
	v_mfma_f32_16x16x32_bf16 v[0:3], v[204:207], v[188:191], v[0:3]
	v_mfma_f32_16x16x32_bf16 v[52:55], v[200:203], v[168:171], v[52:55]
	v_mfma_f32_16x16x32_bf16 v[48:51], v[208:211], v[168:171], v[48:51]
	v_mfma_f32_16x16x32_bf16 v[36:39], v[200:203], v[176:179], v[36:39]
	v_mfma_f32_16x16x32_bf16 v[32:35], v[208:211], v[176:179], v[32:35]
	v_mfma_f32_16x16x32_bf16 v[20:23], v[200:203], v[184:187], v[20:23]
	v_mfma_f32_16x16x32_bf16 v[16:19], v[208:211], v[184:187], v[16:19]
	v_mfma_f32_16x16x32_bf16 v[4:7], v[200:203], v[192:195], v[4:7]
	v_mfma_f32_16x16x32_bf16 v[0:3], v[208:211], v[192:195], v[0:3]
	s_setprio 0
	s_add_i32 s60, 0, 0x18000
	v_add_u32_e32 v160, s60, v143
	s_barrier
	ds_read_b128 v[148:151], v160
	ds_read_b128 v[152:155], v160 offset:1024
	ds_read_b128 v[156:159], v160 offset:2048
	ds_read_b128 v[160:163], v160 offset:3072
	s_add_u32 s36, s36, 0x40000
	s_addc_u32 s37, s37, 0
	s_mov_b32 m0, s45
	v_lshl_add_u64 v[196:197], s[36:37], 0, v[130:131]
	ds_read_b128 v[164:167], v146 offset:32768
	ds_read_b128 v[168:171], v146 offset:33792
	ds_read_b128 v[172:175], v146 offset:34816
	ds_read_b128 v[176:179], v146 offset:35840
	ds_read_b128 v[180:183], v146 offset:36864
	ds_read_b128 v[184:187], v146 offset:37888
	ds_read_b128 v[188:191], v146 offset:38912
	ds_read_b128 v[192:195], v146 offset:39936
	global_load_lds_dwordx4 v[196:197], off
	v_lshl_add_u64 v[196:197], s[36:37], 0, v[128:129]
	s_mov_b32 m0, s46
	s_nop 0
	global_load_lds_dwordx4 v[196:197], off
	s_waitcnt lgkmcnt(8)
	s_barrier
	s_waitcnt lgkmcnt(0)
	s_setprio 1
	s_waitcnt lgkmcnt(0)
	v_mfma_f32_16x16x32_bf16 v[124:127], v[148:151], v[164:167], v[124:127]
	v_mfma_f32_16x16x32_bf16 v[120:123], v[156:159], v[164:167], v[120:123]
	v_mfma_f32_16x16x32_bf16 v[108:111], v[148:151], v[172:175], v[108:111]
	v_mfma_f32_16x16x32_bf16 v[104:107], v[156:159], v[172:175], v[104:107]
	v_mfma_f32_16x16x32_bf16 v[92:95], v[148:151], v[180:183], v[92:95]
	v_mfma_f32_16x16x32_bf16 v[88:91], v[156:159], v[180:183], v[88:91]
	v_mfma_f32_16x16x32_bf16 v[76:79], v[148:151], v[188:191], v[76:79]
	v_mfma_f32_16x16x32_bf16 v[72:75], v[156:159], v[188:191], v[72:75]
	v_mfma_f32_16x16x32_bf16 v[124:127], v[152:155], v[168:171], v[124:127]
	v_mfma_f32_16x16x32_bf16 v[120:123], v[160:163], v[168:171], v[120:123]
	v_mfma_f32_16x16x32_bf16 v[108:111], v[152:155], v[176:179], v[108:111]
	v_mfma_f32_16x16x32_bf16 v[104:107], v[160:163], v[176:179], v[104:107]
	v_mfma_f32_16x16x32_bf16 v[92:95], v[152:155], v[184:187], v[92:95]
	v_mfma_f32_16x16x32_bf16 v[88:91], v[160:163], v[184:187], v[88:91]
	v_mfma_f32_16x16x32_bf16 v[76:79], v[152:155], v[192:195], v[76:79]
	v_mfma_f32_16x16x32_bf16 v[72:75], v[160:163], v[192:195], v[72:75]
	s_setprio 0
	s_barrier
	s_add_i32 s36, 0, 0x1c000
	s_add_i32 s37, s60, s40
	v_add_u32_e32 v208, s36, v143
	v_lshl_add_u64 v[140:141], v[140:141], 0, s[6:7]
	s_mov_b32 m0, s37
	ds_read_b128 v[196:199], v208
	ds_read_b128 v[200:203], v208 offset:1024
	ds_read_b128 v[204:207], v208 offset:2048
	ds_read_b128 v[208:211], v208 offset:3072
	global_load_lds_dwordx4 v[140:141], off
	v_lshl_add_u64 v[140:141], v[212:213], 0, s[6:7]
	s_add_i32 m0, s37, 0x2000
	s_nop 0
	global_load_lds_dwordx4 v[140:141], off
	s_barrier
	s_waitcnt lgkmcnt(0)
	s_setprio 1
	s_waitcnt lgkmcnt(0)
	v_mfma_f32_16x16x32_bf16 v[116:119], v[196:199], v[164:167], v[116:119]
	v_mfma_f32_16x16x32_bf16 v[112:115], v[204:207], v[164:167], v[112:115]
	v_mfma_f32_16x16x32_bf16 v[100:103], v[196:199], v[172:175], v[100:103]
	v_mfma_f32_16x16x32_bf16 v[96:99], v[204:207], v[172:175], v[96:99]
	v_mfma_f32_16x16x32_bf16 v[84:87], v[196:199], v[180:183], v[84:87]
	v_mfma_f32_16x16x32_bf16 v[80:83], v[204:207], v[180:183], v[80:83]
	v_mfma_f32_16x16x32_bf16 v[68:71], v[196:199], v[188:191], v[68:71]
	v_mfma_f32_16x16x32_bf16 v[64:67], v[204:207], v[188:191], v[64:67]
	v_mfma_f32_16x16x32_bf16 v[116:119], v[200:203], v[168:171], v[116:119]
	v_mfma_f32_16x16x32_bf16 v[112:115], v[208:211], v[168:171], v[112:115]
	v_mfma_f32_16x16x32_bf16 v[100:103], v[200:203], v[176:179], v[100:103]
	v_mfma_f32_16x16x32_bf16 v[96:99], v[208:211], v[176:179], v[96:99]
	v_mfma_f32_16x16x32_bf16 v[84:87], v[200:203], v[184:187], v[84:87]
	v_mfma_f32_16x16x32_bf16 v[80:83], v[208:211], v[184:187], v[80:83]
	v_mfma_f32_16x16x32_bf16 v[68:71], v[200:203], v[192:195], v[68:71]
	v_mfma_f32_16x16x32_bf16 v[64:67], v[208:211], v[192:195], v[64:67]
	s_setprio 0
	s_mov_b32 m0, s48
	v_lshl_add_u64 v[140:141], v[214:215], 0, s[6:7]
	s_barrier
	ds_read_b128 v[164:167], v146 offset:49152
	ds_read_b128 v[168:171], v146 offset:50176
	ds_read_b128 v[172:175], v146 offset:51200
	ds_read_b128 v[176:179], v146 offset:52224
	ds_read_b128 v[180:183], v146 offset:53248
	ds_read_b128 v[184:187], v146 offset:54272
	ds_read_b128 v[188:191], v146 offset:55296
	ds_read_b128 v[192:195], v146 offset:56320
	global_load_lds_dwordx4 v[140:141], off
	v_lshl_add_u64 v[140:141], v[216:217], 0, s[6:7]
	s_mov_b32 m0, s49
	s_nop 0
	global_load_lds_dwordx4 v[140:141], off
	s_barrier
; __device__ __forceinline__ float sigmoidf_(float x) { return __builtin_amdgcn_rcpf(1.f + __expf(-x)); }
; #define G8_STAGE(bufoff, gbase, voff) do { _Pragma("unroll") for (int _i = 0; _i < 2; ++_i) \
;     __builtin_amdgcn_global_load_lds((const unsigned*)((const char*)(gbase) + (voff)[_i]), (LAS unsigned*)(lds + (bufoff) + ldsw + _i * 8192), 16, 0, 0); } while (0)
; #define G8_LDA(dst, b, h) do { _Pragma("unroll") for (int m = 0; m < 4; ++m) _Pragma("unroll") for (int k = 0; k < 2; ++k) dst[m][k] = *(const LAS bf16x8*)(lds + G8_SA(b, h) + aoff + m * 2048 + k * 1024); } while (0)
; #define G8_MMA(ai, bj, At, Bt) do { __builtin_amdgcn_s_setprio(1); _Pragma("unroll") for (int m = 0; m < 4; ++m) _Pragma("unroll") for (int n = 0; n < 2; ++n) _Pragma("unroll") for (int k = 0; k < 2; ++k) \
;     acc[ai][bj][m][n] = __builtin_amdgcn_mfma_f32_16x16x32_bf16(Bt[n][k], At[m][k], acc[ai][bj][m][n], 0, 0, 0); __builtin_amdgcn_s_setprio(0); } while (0)
; #define G8_WAIT_V(n) asm volatile("s_waitcnt vmcnt(" #n ")" ::: "memory")
; #define G8_BAR __builtin_amdgcn_s_barrier()
; template <class Epi, class Sched>
; __device__ __forceinline__ void gemm_phase(LAS unsigned char* lds, const Gemm g, const Sched& S, const Epi& E) {
;     ...
;       G8_LDA(At, 1, 1); G8_STAGE(G8_SA(1, 0), a3, voffA);
;       G8_BAR; G8_WAIT_L(0); G8_MMA(1, 0, At, B0); G8_BAR; G8_SCHED;
;       G8_STAGE(G8_SB(1, 1), b3 + hstepB, voffB);
;       G8_WAIT_V(6); G8_BAR; G8_MMA(1, 1, At, B1); G8_BAR;
;   __device__ __forceinline__ void operator()(const f32x4 (&acc)[2][2][4][2], const g8::Unit& u, int wr, int wc, int fr, int fq) const {
; #pragma unroll
;     for (int ai = 0; ai < 2; ++ai)
; #pragma unroll
;       for (int m = 0; m < 4; ++m) {
;         const int row = u.pm * 256 + ai * 128 + wr * 64 + m * 16 + fr;
; #pragma unroll
;         for (int bj = 0; bj < 2; ++bj) {
;           f32x4 v0 = acc[ai][bj][m][0], v1 = acc[ai][bj][m][1];
; #pragma unroll
;           for (int j = 0; j < 4; ++j) {
;             if (ACT == 1) { v0[j] = sigmoidf_(v0[j]); v1[j] = sigmoidf_(v1[j]); }
;             else { float a = fmaxf(v0[j], 0.f), b = fmaxf(v1[j], 0.f); v0[j] = a * a; v1[j] = b * b; }
;           }
;           const int c = u.pn * 256 + bj * 128 + wc * 32 + 8 * fq;
;           bfraw* dst = (c < split) ? (O0 + (size_t)row * ldc + c) : (O1 + (size_t)row * ldc + (c - split));
;           *(uint4*)dst = pack8v(v0, v1);
	s_waitcnt lgkmcnt(0)
	s_setprio 1
	s_waitcnt lgkmcnt(0)
	v_mfma_f32_16x16x32_bf16 v[60:63], v[148:151], v[164:167], v[60:63]
	v_mfma_f32_16x16x32_bf16 v[56:59], v[156:159], v[164:167], v[56:59]
	v_mfma_f32_16x16x32_bf16 v[44:47], v[148:151], v[172:175], v[44:47]
	v_mfma_f32_16x16x32_bf16 v[40:43], v[156:159], v[172:175], v[40:43]
	v_mfma_f32_16x16x32_bf16 v[28:31], v[148:151], v[180:183], v[28:31]
	v_mfma_f32_16x16x32_bf16 v[24:27], v[156:159], v[180:183], v[24:27]
	v_mfma_f32_16x16x32_bf16 v[12:15], v[148:151], v[188:191], v[12:15]
	v_mfma_f32_16x16x32_bf16 v[8:11], v[156:159], v[188:191], v[8:11]
	v_mfma_f32_16x16x32_bf16 v[60:63], v[152:155], v[168:171], v[60:63]
	v_mfma_f32_16x16x32_bf16 v[56:59], v[160:163], v[168:171], v[56:59]
	v_mfma_f32_16x16x32_bf16 v[44:47], v[152:155], v[176:179], v[44:47]
	v_mfma_f32_16x16x32_bf16 v[40:43], v[160:163], v[176:179], v[40:43]
	v_mfma_f32_16x16x32_bf16 v[28:31], v[152:155], v[184:187], v[28:31]
	v_mfma_f32_16x16x32_bf16 v[24:27], v[160:163], v[184:187], v[24:27]
	v_mfma_f32_16x16x32_bf16 v[12:15], v[152:155], v[192:195], v[12:15]
	v_mfma_f32_16x16x32_bf16 v[8:11], v[160:163], v[192:195], v[8:11]
	s_setprio 0
	s_barrier
	s_add_u32 s34, s34, 0x40080
	s_addc_u32 s35, s35, 0
	s_add_i32 s36, s36, s40
	v_lshl_add_u64 v[140:141], s[34:35], 0, v[130:131]
	s_mov_b32 m0, s36
	s_nop 0
	global_load_lds_dwordx4 v[140:141], off
	v_lshl_add_u64 v[140:141], s[34:35], 0, v[128:129]
	s_add_i32 m0, s36, 0x2000
	s_nop 0
	global_load_lds_dwordx4 v[140:141], off
	s_waitcnt vmcnt(6)
	s_barrier
	s_setprio 1
	v_mfma_f32_16x16x32_bf16 v[52:55], v[196:199], v[164:167], v[52:55]
	v_mfma_f32_16x16x32_bf16 v[48:51], v[204:207], v[164:167], v[48:51]
	v_mfma_f32_16x16x32_bf16 v[36:39], v[196:199], v[172:175], v[36:39]
	v_mfma_f32_16x16x32_bf16 v[32:35], v[204:207], v[172:175], v[32:35]
	v_mfma_f32_16x16x32_bf16 v[20:23], v[196:199], v[180:183], v[20:23]
	v_mfma_f32_16x16x32_bf16 v[16:19], v[204:207], v[180:183], v[16:19]
	v_mfma_f32_16x16x32_bf16 v[4:7], v[196:199], v[188:191], v[4:7]
	v_mfma_f32_16x16x32_bf16 v[0:3], v[204:207], v[188:191], v[0:3]
	v_mfma_f32_16x16x32_bf16 v[52:55], v[200:203], v[168:171], v[52:55]
	v_mfma_f32_16x16x32_bf16 v[48:51], v[208:211], v[168:171], v[48:51]
	v_mfma_f32_16x16x32_bf16 v[36:39], v[200:203], v[176:179], v[36:39]
	v_mfma_f32_16x16x32_bf16 v[32:35], v[208:211], v[176:179], v[32:35]
	v_mfma_f32_16x16x32_bf16 v[20:23], v[200:203], v[184:187], v[20:23]
	v_mfma_f32_16x16x32_bf16 v[16:19], v[208:211], v[184:187], v[16:19]
	v_mfma_f32_16x16x32_bf16 v[4:7], v[200:203], v[192:195], v[4:7]
	v_mfma_f32_16x16x32_bf16 v[0:3], v[208:211], v[192:195], v[0:3]
	s_setprio 0
	s_add_i32 s59, s59, 2
	s_add_u32 s30, s30, 0x100
	s_addc_u32 s31, s31, 0
	s_add_u32 s57, s57, 0x100
	s_addc_u32 s58, s58, 0
	s_cmp_gt_u32 s59, 13
	s_barrier
	s_cbranch_scc0 .LBB0_2356
	v_max_f32_e32 v120, 0, v120
	v_mul_f32_e32 v157, v120, v120
	v_max_f32_e32 v120, v125, v125
	v_max_f32_e32 v120, 0, v120
	v_max_f32_e32 v121, 0, v121
	v_mul_f32_e32 v158, v120, v120
	v_mul_f32_e32 v159, v121, v121
	v_max_f32_e32 v120, v126, v126
	v_max_f32_e32 v121, v122, v122
	v_max_f32_e32 v120, 0, v120
	v_max_f32_e32 v121, 0, v121
	v_lshl_add_u32 v140, s4, 8, v142
	v_mul_f32_e32 v160, v120, v120
	v_mul_f32_e32 v126, v121, v121
	v_max_f32_e32 v120, v127, v127
	v_max_f32_e32 v121, v123, v123
	v_lshl_or_b32 v148, s5, 8, v144
	v_ashrrev_i32_e32 v141, 31, v140
	v_max_f32_e32 v120, 0, v120
	v_max_f32_e32 v121, 0, v121
	v_max_f32_e32 v124, 0, v124
	v_mul_f32_e32 v161, v120, v120
	v_mul_f32_e32 v127, v121, v121
	v_lshlrev_b64 v[120:121], 13, v[140:141]
	v_ashrrev_i32_e32 v149, 31, v148
	v_mul_f32_e32 v156, v124, v124
	v_lshl_add_u64 v[124:125], s[0:1], 0, v[120:121]
	v_lshlrev_b64 v[120:121], 1, v[148:149]
	v_mov_b32_e32 v149, v131
	v_lshlrev_b64 v[122:123], 1, v[148:149]
	v_lshl_add_u64 v[152:153], v[124:125], 0, v[122:123]
	v_lshl_add_u64 v[150:151], v[124:125], 0, v[120:121]
	v_lshl_add_u64 v[124:125], v[152:153], 0, s[10:11]
	v_cmp_gt_i32_e32 vcc, 2.0, v148
	v_cvt_pk_bf16_f32 v127, v126, v127
	v_cndmask_b32_e32 v155, v125, v151, vcc
	v_cndmask_b32_e32 v154, v124, v150, vcc
	v_cvt_pk_bf16_f32 v126, v157, v159
	v_cvt_pk_bf16_f32 v125, v160, v161
	v_cvt_pk_bf16_f32 v124, v156, v158
	v_max_f32_e32 v112, 0, v112
	global_store_dwordx4 v[154:155], v[124:127], off
	v_max_f32_e32 v113, 0, v113
	v_mul_f32_e32 v125, v112, v112
	v_max_f32_e32 v112, v117, v117
	v_max_f32_e32 v112, 0, v112
	v_mul_f32_e32 v126, v112, v112
	v_mul_f32_e32 v127, v113, v113
	v_max_f32_e32 v112, v118, v118
	v_max_f32_e32 v113, v114, v114
	v_max_f32_e32 v112, 0, v112
	v_max_f32_e32 v113, 0, v113
	v_max_f32_e32 v116, 0, v116
	v_mul_f32_e32 v118, v112, v112
	v_mul_f32_e32 v141, v113, v113
	v_max_f32_e32 v112, v119, v119
	v_max_f32_e32 v113, v115, v115
	v_mul_f32_e32 v124, v116, v116
	v_max_f32_e32 v112, 0, v112
	v_max_f32_e32 v113, 0, v113
	v_or_b32_e32 v116, 0x80, v148
	v_mul_f32_e32 v119, v112, v112
	v_mul_f32_e32 v149, v113, v113
	v_lshl_add_u64 v[112:113], v[150:151], 0, s[8:9]
	v_lshl_add_u64 v[114:115], v[152:153], 0, s[12:13]
	v_cmp_gt_i32_e64 s[4:5], 2.0, v116
	v_max_f32_e32 v104, 0, v104
	v_cndmask_b32_e64 v117, v115, v113, s[4:5]
	v_cndmask_b32_e64 v116, v114, v112, s[4:5]
	v_cvt_pk_bf16_f32 v115, v141, v149
	v_cvt_pk_bf16_f32 v114, v125, v127
	v_cvt_pk_bf16_f32 v113, v118, v119
	v_cvt_pk_bf16_f32 v112, v124, v126
	global_store_dwordx4 v[116:117], v[112:115], off
	v_max_f32_e32 v105, 0, v105
	v_mul_f32_e32 v115, v104, v104
	v_max_f32_e32 v104, v109, v109
	v_max_f32_e32 v104, 0, v104
	v_mul_f32_e32 v116, v104, v104
	v_mul_f32_e32 v117, v105, v105
	v_max_f32_e32 v104, v110, v110
; __device__ __forceinline__ float sigmoidf_(float x) { return __builtin_amdgcn_rcpf(1.f + __expf(-x)); }
;   __device__ __forceinline__ void operator()(const f32x4 (&acc)[2][2][4][2], const g8::Unit& u, int wr, int wc, int fr, int fq) const {
;     ...
;           for (int j = 0; j < 4; ++j) {
;             if (ACT == 1) { v0[j] = sigmoidf_(v0[j]); v1[j] = sigmoidf_(v1[j]); }
;             else { float a = fmaxf(v0[j], 0.f), b = fmaxf(v1[j], 0.f); v0[j] = a * a; v1[j] = b * b; }
;           }
;           const int c = u.pn * 256 + bj * 128 + wc * 32 + 8 * fq;
;           bfraw* dst = (c < split) ? (O0 + (size_t)row * ldc + c) : (O1 + (size_t)row * ldc + (c - split));
;           *(uint4*)dst = pack8v(v0, v1);
	v_max_f32_e32 v105, v106, v106
	v_max_f32_e32 v104, 0, v104
	v_max_f32_e32 v105, 0, v105
	v_or_b32_e32 v112, 16, v140
	v_mul_f32_e32 v118, v104, v104
	v_mul_f32_e32 v106, v105, v105
	v_max_f32_e32 v104, v111, v111
	v_max_f32_e32 v105, v107, v107
	v_ashrrev_i32_e32 v113, 31, v112
	v_max_f32_e32 v104, 0, v104
	v_max_f32_e32 v105, 0, v105
	v_mul_f32_e32 v119, v104, v104
	v_mul_f32_e32 v107, v105, v105
	v_lshlrev_b64 v[104:105], 13, v[112:113]
	v_lshl_add_u64 v[104:105], s[0:1], 0, v[104:105]
	v_max_f32_e32 v108, 0, v108
	v_lshl_add_u64 v[110:111], v[104:105], 0, v[122:123]
	v_mul_f32_e32 v114, v108, v108
	v_lshl_add_u64 v[108:109], v[104:105], 0, v[120:121]
	v_lshl_add_u64 v[104:105], v[110:111], 0, s[10:11]
	v_cndmask_b32_e32 v113, v105, v109, vcc
	v_cndmask_b32_e32 v112, v104, v108, vcc
	v_cvt_pk_bf16_f32 v107, v106, v107
	v_cvt_pk_bf16_f32 v106, v115, v117
	v_cvt_pk_bf16_f32 v105, v118, v119
	v_cvt_pk_bf16_f32 v104, v114, v116
	v_max_f32_e32 v96, 0, v96
	global_store_dwordx4 v[112:113], v[104:107], off
	v_max_f32_e32 v97, 0, v97
	v_mul_f32_e32 v105, v96, v96
	v_max_f32_e32 v96, v101, v101
	v_max_f32_e32 v96, 0, v96
	v_mul_f32_e32 v106, v96, v96
	v_mul_f32_e32 v107, v97, v97
	v_max_f32_e32 v96, v102, v102
	v_max_f32_e32 v97, v98, v98
	v_max_f32_e32 v96, 0, v96
	v_max_f32_e32 v97, 0, v97
	v_mul_f32_e32 v102, v96, v96
	v_mul_f32_e32 v112, v97, v97
	v_max_f32_e32 v96, v103, v103
	v_max_f32_e32 v97, v99, v99
	v_max_f32_e32 v100, 0, v100
	v_max_f32_e32 v96, 0, v96
	v_max_f32_e32 v97, 0, v97
	v_mul_f32_e32 v104, v100, v100
	v_mul_f32_e32 v103, v96, v96
	v_mul_f32_e32 v113, v97, v97
	v_lshl_add_u64 v[96:97], v[108:109], 0, s[8:9]
	v_lshl_add_u64 v[98:99], v[110:111], 0, s[12:13]
	v_cndmask_b32_e64 v101, v99, v97, s[4:5]
	v_cndmask_b32_e64 v100, v98, v96, s[4:5]
	v_cvt_pk_bf16_f32 v99, v112, v113
	v_cvt_pk_bf16_f32 v98, v105, v107
	v_cvt_pk_bf16_f32 v97, v102, v103
	v_cvt_pk_bf16_f32 v96, v104, v106
	v_max_f32_e32 v88, 0, v88
	global_store_dwordx4 v[100:101], v[96:99], off
	v_max_f32_e32 v89, 0, v89
	v_mul_f32_e32 v99, v88, v88
	v_max_f32_e32 v88, v93, v93
	v_max_f32_e32 v88, 0, v88
	v_mul_f32_e32 v100, v88, v88
	v_mul_f32_e32 v101, v89, v89
	v_max_f32_e32 v88, v94, v94
	v_max_f32_e32 v89, v90, v90
	v_max_f32_e32 v88, 0, v88
	v_max_f32_e32 v89, 0, v89
	v_or_b32_e32 v96, 32, v140
	v_mul_f32_e32 v102, v88, v88
	v_mul_f32_e32 v90, v89, v89
	v_max_f32_e32 v88, v95, v95
	v_max_f32_e32 v89, v91, v91
	v_ashrrev_i32_e32 v97, 31, v96
	v_max_f32_e32 v88, 0, v88
	v_max_f32_e32 v89, 0, v89
	v_mul_f32_e32 v103, v88, v88
	v_mul_f32_e32 v91, v89, v89
	v_lshlrev_b64 v[88:89], 13, v[96:97]
	v_lshl_add_u64 v[88:89], s[0:1], 0, v[88:89]
	v_max_f32_e32 v92, 0, v92
	v_lshl_add_u64 v[94:95], v[88:89], 0, v[122:123]
	v_mul_f32_e32 v98, v92, v92
	v_lshl_add_u64 v[92:93], v[88:89], 0, v[120:121]
	v_lshl_add_u64 v[88:89], v[94:95], 0, s[10:11]
	v_cndmask_b32_e32 v97, v89, v93, vcc
	v_cndmask_b32_e32 v96, v88, v92, vcc
	v_cvt_pk_bf16_f32 v91, v90, v91
	v_cvt_pk_bf16_f32 v90, v99, v101
	v_cvt_pk_bf16_f32 v89, v102, v103
	v_cvt_pk_bf16_f32 v88, v98, v100
	v_max_f32_e32 v80, 0, v80
	global_store_dwordx4 v[96:97], v[88:91], off
	v_max_f32_e32 v81, 0, v81
	v_mul_f32_e32 v89, v80, v80
	v_max_f32_e32 v80, v85, v85
	v_max_f32_e32 v80, 0, v80
	v_mul_f32_e32 v90, v80, v80
	v_mul_f32_e32 v91, v81, v81
	v_max_f32_e32 v80, v86, v86
	v_max_f32_e32 v81, v82, v82
	v_max_f32_e32 v80, 0, v80
	v_max_f32_e32 v81, 0, v81
	v_mul_f32_e32 v86, v80, v80
	v_mul_f32_e32 v96, v81, v81
	v_max_f32_e32 v80, v87, v87
	v_max_f32_e32 v81, v83, v83
	v_max_f32_e32 v84, 0, v84
	v_max_f32_e32 v80, 0, v80
	v_max_f32_e32 v81, 0, v81
	v_mul_f32_e32 v88, v84, v84
	v_mul_f32_e32 v87, v80, v80
	v_mul_f32_e32 v97, v81, v81
	v_lshl_add_u64 v[80:81], v[92:93], 0, s[8:9]
	v_lshl_add_u64 v[82:83], v[94:95], 0, s[12:13]
	v_cndmask_b32_e64 v85, v83, v81, s[4:5]
	v_cndmask_b32_e64 v84, v82, v80, s[4:5]
	v_cvt_pk_bf16_f32 v83, v96, v97
	v_cvt_pk_bf16_f32 v82, v89, v91
	v_cvt_pk_bf16_f32 v81, v86, v87
	v_cvt_pk_bf16_f32 v80, v88, v90
	v_max_f32_e32 v72, 0, v72
	global_store_dwordx4 v[84:85], v[80:83], off
	v_max_f32_e32 v73, 0, v73
	v_mul_f32_e32 v83, v72, v72
	v_max_f32_e32 v72, v77, v77
	v_max_f32_e32 v72, 0, v72
	v_mul_f32_e32 v84, v72, v72
	v_mul_f32_e32 v85, v73, v73
	v_max_f32_e32 v72, v78, v78
	v_max_f32_e32 v73, v74, v74
	v_max_f32_e32 v72, 0, v72
	v_max_f32_e32 v73, 0, v73
	v_or_b32_e32 v80, 48, v140
	v_mul_f32_e32 v86, v72, v72
	v_mul_f32_e32 v74, v73, v73
	v_max_f32_e32 v72, v79, v79
	v_max_f32_e32 v73, v75, v75
	v_ashrrev_i32_e32 v81, 31, v80
	v_max_f32_e32 v72, 0, v72
	v_max_f32_e32 v73, 0, v73
	v_mul_f32_e32 v87, v72, v72
	v_mul_f32_e32 v75, v73, v73
	v_lshlrev_b64 v[72:73], 13, v[80:81]
	v_lshl_add_u64 v[72:73], s[0:1], 0, v[72:73]
	v_max_f32_e32 v76, 0, v76
	v_lshl_add_u64 v[78:79], v[72:73], 0, v[122:123]
	v_mul_f32_e32 v82, v76, v76
	v_lshl_add_u64 v[76:77], v[72:73], 0, v[120:121]
	v_lshl_add_u64 v[72:73], v[78:79], 0, s[10:11]
	v_cndmask_b32_e32 v81, v73, v77, vcc
	v_cndmask_b32_e32 v80, v72, v76, vcc
	v_cvt_pk_bf16_f32 v75, v74, v75
	v_cvt_pk_bf16_f32 v74, v83, v85
	v_cvt_pk_bf16_f32 v73, v86, v87
	v_cvt_pk_bf16_f32 v72, v82, v84
	v_max_f32_e32 v64, 0, v64
	global_store_dwordx4 v[80:81], v[72:75], off
	v_max_f32_e32 v65, 0, v65
	v_mul_f32_e32 v73, v64, v64
	v_max_f32_e32 v64, v69, v69
	v_max_f32_e32 v64, 0, v64
	v_mul_f32_e32 v74, v64, v64
	v_mul_f32_e32 v75, v65, v65
	v_max_f32_e32 v64, v70, v70
	v_max_f32_e32 v65, v66, v66
	v_max_f32_e32 v64, 0, v64
	v_max_f32_e32 v65, 0, v65
	v_mul_f32_e32 v70, v64, v64
	v_mul_f32_e32 v80, v65, v65
	v_max_f32_e32 v64, v71, v71
	v_max_f32_e32 v65, v67, v67
; __device__ __forceinline__ float sigmoidf_(float x) { return __builtin_amdgcn_rcpf(1.f + __expf(-x)); }
;   __device__ __forceinline__ void operator()(const f32x4 (&acc)[2][2][4][2], const g8::Unit& u, int wr, int wc, int fr, int fq) const {
;     ...
;           for (int j = 0; j < 4; ++j) {
;             if (ACT == 1) { v0[j] = sigmoidf_(v0[j]); v1[j] = sigmoidf_(v1[j]); }
;             else { float a = fmaxf(v0[j], 0.f), b = fmaxf(v1[j], 0.f); v0[j] = a * a; v1[j] = b * b; }
;           }
;           const int c = u.pn * 256 + bj * 128 + wc * 32 + 8 * fq;
;           bfraw* dst = (c < split) ? (O0 + (size_t)row * ldc + c) : (O1 + (size_t)row * ldc + (c - split));
;           *(uint4*)dst = pack8v(v0, v1);
	v_max_f32_e32 v68, 0, v68
	v_max_f32_e32 v64, 0, v64
	v_max_f32_e32 v65, 0, v65
	v_mul_f32_e32 v72, v68, v68
	v_mul_f32_e32 v71, v64, v64
	v_mul_f32_e32 v81, v65, v65
	v_lshl_add_u64 v[64:65], v[76:77], 0, s[8:9]
	v_lshl_add_u64 v[66:67], v[78:79], 0, s[12:13]
	v_cndmask_b32_e64 v69, v67, v65, s[4:5]
	v_cndmask_b32_e64 v68, v66, v64, s[4:5]
	v_cvt_pk_bf16_f32 v67, v80, v81
	v_cvt_pk_bf16_f32 v66, v73, v75
	v_cvt_pk_bf16_f32 v65, v70, v71
	v_cvt_pk_bf16_f32 v64, v72, v74
	v_max_f32_e32 v56, 0, v56
	global_store_dwordx4 v[68:69], v[64:67], off
	v_max_f32_e32 v57, 0, v57
	v_mul_f32_e32 v67, v56, v56
	v_max_f32_e32 v56, v61, v61
	v_max_f32_e32 v56, 0, v56
	v_mul_f32_e32 v68, v56, v56
	v_mul_f32_e32 v69, v57, v57
	v_max_f32_e32 v56, v62, v62
	v_max_f32_e32 v57, v58, v58
	v_max_f32_e32 v56, 0, v56
	v_max_f32_e32 v57, 0, v57
	v_add_u32_e32 v64, 0x80, v140
	v_mul_f32_e32 v70, v56, v56
	v_mul_f32_e32 v58, v57, v57
	v_max_f32_e32 v56, v63, v63
	v_max_f32_e32 v57, v59, v59
	v_ashrrev_i32_e32 v65, 31, v64
	v_max_f32_e32 v56, 0, v56
	v_max_f32_e32 v57, 0, v57
	v_mul_f32_e32 v71, v56, v56
	v_mul_f32_e32 v59, v57, v57
	v_lshlrev_b64 v[56:57], 13, v[64:65]
	v_lshl_add_u64 v[56:57], s[0:1], 0, v[56:57]
	v_max_f32_e32 v60, 0, v60
	v_lshl_add_u64 v[62:63], v[56:57], 0, v[122:123]
	v_mul_f32_e32 v66, v60, v60
	v_lshl_add_u64 v[60:61], v[56:57], 0, v[120:121]
	v_lshl_add_u64 v[56:57], v[62:63], 0, s[10:11]
	v_cndmask_b32_e32 v65, v57, v61, vcc
	v_cndmask_b32_e32 v64, v56, v60, vcc
	v_cvt_pk_bf16_f32 v59, v58, v59
	v_cvt_pk_bf16_f32 v58, v67, v69
	v_cvt_pk_bf16_f32 v57, v70, v71
	v_cvt_pk_bf16_f32 v56, v66, v68
	v_max_f32_e32 v48, 0, v48
	global_store_dwordx4 v[64:65], v[56:59], off
	v_max_f32_e32 v49, 0, v49
	v_mul_f32_e32 v57, v48, v48
	v_max_f32_e32 v48, v53, v53
	v_max_f32_e32 v48, 0, v48
	v_mul_f32_e32 v58, v48, v48
	v_mul_f32_e32 v59, v49, v49
	v_max_f32_e32 v48, v54, v54
	v_max_f32_e32 v49, v50, v50
	v_max_f32_e32 v48, 0, v48
	v_max_f32_e32 v49, 0, v49
	v_mul_f32_e32 v54, v48, v48
	v_mul_f32_e32 v64, v49, v49
	v_max_f32_e32 v48, v55, v55
	v_max_f32_e32 v49, v51, v51
	v_max_f32_e32 v52, 0, v52
	v_max_f32_e32 v48, 0, v48
	v_max_f32_e32 v49, 0, v49
	v_mul_f32_e32 v56, v52, v52
	v_mul_f32_e32 v55, v48, v48
	v_mul_f32_e32 v65, v49, v49
	v_lshl_add_u64 v[48:49], v[60:61], 0, s[8:9]
	v_lshl_add_u64 v[50:51], v[62:63], 0, s[12:13]
	v_cndmask_b32_e64 v53, v51, v49, s[4:5]
	v_cndmask_b32_e64 v52, v50, v48, s[4:5]
	v_cvt_pk_bf16_f32 v51, v64, v65
	v_cvt_pk_bf16_f32 v50, v57, v59
	v_cvt_pk_bf16_f32 v49, v54, v55
	v_cvt_pk_bf16_f32 v48, v56, v58
	v_max_f32_e32 v40, 0, v40
	global_store_dwordx4 v[52:53], v[48:51], off
	v_max_f32_e32 v41, 0, v41
	v_mul_f32_e32 v51, v40, v40
	v_max_f32_e32 v40, v45, v45
	v_max_f32_e32 v40, 0, v40
	v_mul_f32_e32 v52, v40, v40
	v_mul_f32_e32 v53, v41, v41
	v_max_f32_e32 v40, v46, v46
	v_max_f32_e32 v41, v42, v42
	v_max_f32_e32 v40, 0, v40
	v_max_f32_e32 v41, 0, v41
	v_add_u32_e32 v48, 0x90, v140
	v_mul_f32_e32 v54, v40, v40
	v_mul_f32_e32 v42, v41, v41
	v_max_f32_e32 v40, v47, v47
	v_max_f32_e32 v41, v43, v43
	v_ashrrev_i32_e32 v49, 31, v48
	v_max_f32_e32 v40, 0, v40
	v_max_f32_e32 v41, 0, v41
	v_mul_f32_e32 v55, v40, v40
	v_mul_f32_e32 v43, v41, v41
	v_lshlrev_b64 v[40:41], 13, v[48:49]
	v_lshl_add_u64 v[40:41], s[0:1], 0, v[40:41]
	v_max_f32_e32 v44, 0, v44
	v_lshl_add_u64 v[46:47], v[40:41], 0, v[122:123]
	v_mul_f32_e32 v50, v44, v44
	v_lshl_add_u64 v[44:45], v[40:41], 0, v[120:121]
	v_lshl_add_u64 v[40:41], v[46:47], 0, s[10:11]
	v_cndmask_b32_e32 v49, v41, v45, vcc
	v_cndmask_b32_e32 v48, v40, v44, vcc
	v_cvt_pk_bf16_f32 v43, v42, v43
	v_cvt_pk_bf16_f32 v42, v51, v53
	v_cvt_pk_bf16_f32 v41, v54, v55
	v_cvt_pk_bf16_f32 v40, v50, v52
	v_max_f32_e32 v32, 0, v32
	global_store_dwordx4 v[48:49], v[40:43], off
	v_max_f32_e32 v33, 0, v33
	v_mul_f32_e32 v41, v32, v32
	v_max_f32_e32 v32, v37, v37
	v_max_f32_e32 v32, 0, v32
	v_mul_f32_e32 v42, v32, v32
	v_mul_f32_e32 v43, v33, v33
	v_max_f32_e32 v32, v38, v38
	v_max_f32_e32 v33, v34, v34
	v_max_f32_e32 v32, 0, v32
	v_max_f32_e32 v33, 0, v33
	v_mul_f32_e32 v38, v32, v32
	v_mul_f32_e32 v48, v33, v33
	v_max_f32_e32 v32, v39, v39
	v_max_f32_e32 v33, v35, v35
	v_max_f32_e32 v36, 0, v36
	v_max_f32_e32 v32, 0, v32
	v_max_f32_e32 v33, 0, v33
	v_mul_f32_e32 v40, v36, v36
	v_mul_f32_e32 v39, v32, v32
	v_mul_f32_e32 v49, v33, v33
	v_lshl_add_u64 v[32:33], v[44:45], 0, s[8:9]
	v_lshl_add_u64 v[34:35], v[46:47], 0, s[12:13]
; __device__ __forceinline__ float sigmoidf_(float x) { return __builtin_amdgcn_rcpf(1.f + __expf(-x)); }
; template <class Epi, class Sched>
; __device__ __forceinline__ void gemm_phase(LAS unsigned char* lds, const Gemm g, const Sched& S, const Epi& E) {
;     ...
;     E(acc, cur, wr, wc, fr, fq);
;     if (!has_next) break;
;   __device__ __forceinline__ void operator()(const f32x4 (&acc)[2][2][4][2], const g8::Unit& u, int wr, int wc, int fr, int fq) const {
;     ...
;           for (int j = 0; j < 4; ++j) {
;             if (ACT == 1) { v0[j] = sigmoidf_(v0[j]); v1[j] = sigmoidf_(v1[j]); }
;             else { float a = fmaxf(v0[j], 0.f), b = fmaxf(v1[j], 0.f); v0[j] = a * a; v1[j] = b * b; }
;           }
;           const int c = u.pn * 256 + bj * 128 + wc * 32 + 8 * fq;
;           bfraw* dst = (c < split) ? (O0 + (size_t)row * ldc + c) : (O1 + (size_t)row * ldc + (c - split));
;           *(uint4*)dst = pack8v(v0, v1);
	v_cndmask_b32_e64 v37, v35, v33, s[4:5]
	v_cndmask_b32_e64 v36, v34, v32, s[4:5]
	v_cvt_pk_bf16_f32 v35, v48, v49
	v_cvt_pk_bf16_f32 v34, v41, v43
	v_cvt_pk_bf16_f32 v33, v38, v39
	v_cvt_pk_bf16_f32 v32, v40, v42
	v_max_f32_e32 v24, 0, v24
	global_store_dwordx4 v[36:37], v[32:35], off
	v_max_f32_e32 v25, 0, v25
	v_mul_f32_e32 v35, v24, v24
	v_max_f32_e32 v24, v29, v29
	v_max_f32_e32 v24, 0, v24
	v_mul_f32_e32 v36, v24, v24
	v_mul_f32_e32 v37, v25, v25
	v_max_f32_e32 v24, v30, v30
	v_max_f32_e32 v25, v26, v26
	v_max_f32_e32 v24, 0, v24
	v_max_f32_e32 v25, 0, v25
	v_add_u32_e32 v32, 0xa0, v140
	v_mul_f32_e32 v38, v24, v24
	v_mul_f32_e32 v26, v25, v25
	v_max_f32_e32 v24, v31, v31
	v_max_f32_e32 v25, v27, v27
	v_ashrrev_i32_e32 v33, 31, v32
	v_max_f32_e32 v24, 0, v24
	v_max_f32_e32 v25, 0, v25
	v_mul_f32_e32 v39, v24, v24
	v_mul_f32_e32 v27, v25, v25
	v_lshlrev_b64 v[24:25], 13, v[32:33]
	v_lshl_add_u64 v[24:25], s[0:1], 0, v[24:25]
	v_max_f32_e32 v28, 0, v28
	v_lshl_add_u64 v[30:31], v[24:25], 0, v[122:123]
	v_mul_f32_e32 v34, v28, v28
	v_lshl_add_u64 v[28:29], v[24:25], 0, v[120:121]
	v_lshl_add_u64 v[24:25], v[30:31], 0, s[10:11]
	v_cndmask_b32_e32 v33, v25, v29, vcc
	v_cndmask_b32_e32 v32, v24, v28, vcc
	v_cvt_pk_bf16_f32 v27, v26, v27
	v_cvt_pk_bf16_f32 v26, v35, v37
	v_cvt_pk_bf16_f32 v25, v38, v39
	v_cvt_pk_bf16_f32 v24, v34, v36
	v_max_f32_e32 v16, 0, v16
	global_store_dwordx4 v[32:33], v[24:27], off
	v_max_f32_e32 v17, 0, v17
	v_mul_f32_e32 v25, v16, v16
	v_max_f32_e32 v16, v21, v21
	v_max_f32_e32 v16, 0, v16
	v_mul_f32_e32 v26, v16, v16
	v_mul_f32_e32 v27, v17, v17
	v_max_f32_e32 v16, v22, v22
	v_max_f32_e32 v17, v18, v18
	v_max_f32_e32 v16, 0, v16
	v_max_f32_e32 v17, 0, v17
	v_mul_f32_e32 v22, v16, v16
	v_mul_f32_e32 v32, v17, v17
	v_max_f32_e32 v16, v23, v23
	v_max_f32_e32 v17, v19, v19
	v_max_f32_e32 v20, 0, v20
	v_max_f32_e32 v16, 0, v16
	v_max_f32_e32 v17, 0, v17
	v_mul_f32_e32 v24, v20, v20
	v_mul_f32_e32 v23, v16, v16
	v_mul_f32_e32 v33, v17, v17
	v_lshl_add_u64 v[16:17], v[28:29], 0, s[8:9]
	v_lshl_add_u64 v[18:19], v[30:31], 0, s[12:13]
	v_cndmask_b32_e64 v21, v19, v17, s[4:5]
	v_cndmask_b32_e64 v20, v18, v16, s[4:5]
	v_cvt_pk_bf16_f32 v19, v32, v33
	v_cvt_pk_bf16_f32 v18, v25, v27
	v_cvt_pk_bf16_f32 v17, v22, v23
	v_cvt_pk_bf16_f32 v16, v24, v26
	v_max_f32_e32 v8, 0, v8
	global_store_dwordx4 v[20:21], v[16:19], off
	v_max_f32_e32 v9, 0, v9
	v_mul_f32_e32 v19, v8, v8
	v_max_f32_e32 v8, v13, v13
	v_max_f32_e32 v8, 0, v8
	v_mul_f32_e32 v20, v8, v8
	v_mul_f32_e32 v21, v9, v9
	v_max_f32_e32 v8, v14, v14
	v_max_f32_e32 v9, v10, v10
	v_max_f32_e32 v8, 0, v8
	v_max_f32_e32 v9, 0, v9
	v_add_u32_e32 v16, 0xb0, v140
	v_mul_f32_e32 v22, v8, v8
	v_mul_f32_e32 v10, v9, v9
	v_max_f32_e32 v8, v15, v15
	v_max_f32_e32 v9, v11, v11
	v_ashrrev_i32_e32 v17, 31, v16
	v_max_f32_e32 v8, 0, v8
	v_max_f32_e32 v9, 0, v9
	v_mul_f32_e32 v23, v8, v8
	v_mul_f32_e32 v11, v9, v9
	v_lshlrev_b64 v[8:9], 13, v[16:17]
	v_lshl_add_u64 v[8:9], s[0:1], 0, v[8:9]
	v_max_f32_e32 v12, 0, v12
	v_lshl_add_u64 v[14:15], v[8:9], 0, v[122:123]
	v_mul_f32_e32 v18, v12, v12
	v_lshl_add_u64 v[12:13], v[8:9], 0, v[120:121]
	v_lshl_add_u64 v[8:9], v[14:15], 0, s[10:11]
	v_cndmask_b32_e32 v17, v9, v13, vcc
	v_cndmask_b32_e32 v16, v8, v12, vcc
	v_cvt_pk_bf16_f32 v11, v10, v11
	v_cvt_pk_bf16_f32 v10, v19, v21
	v_cvt_pk_bf16_f32 v9, v22, v23
	v_cvt_pk_bf16_f32 v8, v18, v20
	v_max_f32_e32 v3, 0, v3
	v_max_f32_e32 v7, 0, v7
	v_max_f32_e32 v0, 0, v0
	v_max_f32_e32 v1, 0, v1
	v_max_f32_e32 v2, 0, v2
	v_max_f32_e32 v4, 0, v4
	v_max_f32_e32 v5, 0, v5
	v_max_f32_e32 v6, 0, v6
	global_store_dwordx4 v[16:17], v[8:11], off
	v_mul_f32_e32 v3, v3, v3
	v_mul_f32_e32 v7, v7, v7
	v_lshl_add_u64 v[8:9], v[12:13], 0, s[8:9]
	v_lshl_add_u64 v[10:11], v[14:15], 0, s[12:13]
	v_mul_f32_e32 v0, v0, v0
	v_mul_f32_e32 v1, v1, v1
	v_mul_f32_e32 v2, v2, v2
	v_mul_f32_e32 v4, v4, v4
	v_mul_f32_e32 v5, v5, v5
	v_mul_f32_e32 v6, v6, v6
	v_cndmask_b32_e64 v9, v11, v9, s[4:5]
	v_cndmask_b32_e64 v8, v10, v8, s[4:5]
	v_cvt_pk_bf16_f32 v3, v2, v3
	v_cvt_pk_bf16_f32 v2, v0, v1
	v_cvt_pk_bf16_f32 v1, v6, v7
	v_cvt_pk_bf16_f32 v0, v4, v5
	s_and_b64 vcc, exec, s[2:3]
	s_mov_b32 s5, s14
	s_mov_b32 s4, s16
	s_mov_b64 s[34:35], s[28:29]
	s_mov_b64 s[30:31], s[18:19]
	global_store_dwordx4 v[8:9], v[0:3], off
	s_cbranch_vccz .LBB0_2353
	s_waitcnt vmcnt(0)
	s_cmpk_gt_u32 s20, 0xff
	s_cbranch_scc1 .LBB0_2360
	s_barrier
